# P0: x to bf16 conversion rewritten as an unpredicated double-buffered stream (16-32 loads in flight per thread, counted vmcnt)
# baseline (speedup 1.0000x reference)
; #define KIN(i) ((const float*)karg(i))
; __device__ __forceinline__ unsigned pk2(float lo, float hi) { const bf16x2_t v = __builtin_convertvector((f32x2_t){lo, hi}, bf16x2_t); return __builtin_bit_cast(unsigned, v); }
; __device__ __forceinline__ void phase0(LAS unsigned char* lds, int wave) {
;     ...
;     bf16_t* Xb = (bf16_t*)(ws + WS_XB);
;     const float* xp = KIN(0); const float* xs = KIN(1);
;     const size_t gt = (size_t)blockIdx.x * 512 + tid, NT = (size_t)gridDim.x * 512, NCH = (size_t)NTOK * DM / 8;
;     for (size_t i = gt; i < NCH; i += 4 * NT) {
;         f32x4 va[4], vb[4];
; #pragma unroll
;         for (int k = 0; k < 4; ++k) {
;             const size_t ii = i + k * NT;
;             if (ii < NCH) { const size_t e = ii * 8; const float* s = e < (size_t)NPROMPT * DM ? xp + e : xs + (e - (size_t)NPROMPT * DM);
;                 va[k] = *(const f32x4*)s; vb[k] = *(const f32x4*)(s + 4); }
;         }
;         __builtin_amdgcn_sched_barrier(0);
; #pragma unroll
;         for (int k = 0; k < 4; ++k) {
;             const size_t ii = i + k * NT;
;             if (ii < NCH) { u32x4 o; o.x = pk2(va[k].x, va[k].y); o.y = pk2(va[k].z, va[k].w); o.z = pk2(vb[k].x, vb[k].y); o.w = pk2(vb[k].z, vb[k].w);
;                 *(u32x4*)(Xb + ii * 8) = o; }
;         }
;     }
.LBB0_19:
	s_load_dwordx2 s[8:9], s[0:1], 0x0
	s_load_dwordx2 s[10:11], s[0:1], 0x8
	s_waitcnt vmcnt(0)
	v_add_u32_e32 v2, s71, v131
	s_mov_b32 s3, 0
	s_lshl_b64 s[28:29], s[2:3], 9
	v_ashrrev_i32_e32 v3, 31, v2
	v_lshl_add_u64 v[58:59], s[28:29], 0, v[2:3]
	s_mov_b64 s[12:13], 0x420000
	v_cmp_gt_u64_e32 vcc, s[12:13], v[58:59]
	s_and_saveexec_b64 s[14:15], vcc
	s_cbranch_execz .LBB0_34
	s_waitcnt lgkmcnt(0)
	s_add_u32 s16, s6, 0x16400000
	s_addc_u32 s17, s7, 0
	v_lshlrev_b32_e32 v34, 5, v58
	v_lshlrev_b32_e32 v35, 4, v58
	s_mov_b64 s[20:21], s[8:9]
	s_mov_b64 s[22:23], s[16:17]
	global_load_dwordx4 v[64:67], v34, s[20:21]
	global_load_dwordx4 v[68:71], v34, s[20:21] offset:16
	s_add_u32 s20, s20, 0x400000
	s_addc_u32 s21, s21, 0
	global_load_dwordx4 v[72:75], v34, s[20:21]
	global_load_dwordx4 v[76:79], v34, s[20:21] offset:16
	s_add_u32 s20, s20, 0x400000
	s_addc_u32 s21, s21, 0
	global_load_dwordx4 v[80:83], v34, s[20:21]
	global_load_dwordx4 v[84:87], v34, s[20:21] offset:16
	s_add_u32 s20, s20, 0x400000
	s_addc_u32 s21, s21, 0
	global_load_dwordx4 v[88:91], v34, s[20:21]
	global_load_dwordx4 v[92:95], v34, s[20:21] offset:16
	s_add_u32 s20, s20, 0x400000
	s_addc_u32 s21, s21, 0
	global_load_dwordx4 v[96:99], v34, s[20:21]
	global_load_dwordx4 v[100:103], v34, s[20:21] offset:16
	s_add_u32 s20, s20, 0x400000
	s_addc_u32 s21, s21, 0
	global_load_dwordx4 v[104:107], v34, s[20:21]
	global_load_dwordx4 v[108:111], v34, s[20:21] offset:16
	s_add_u32 s20, s20, 0x400000
	s_addc_u32 s21, s21, 0
	global_load_dwordx4 v[112:115], v34, s[20:21]
	global_load_dwordx4 v[116:119], v34, s[20:21] offset:16
	s_add_u32 s20, s20, 0x400000
	s_addc_u32 s21, s21, 0
	global_load_dwordx4 v[120:123], v34, s[20:21]
	global_load_dwordx4 v[124:127], v34, s[20:21] offset:16
	s_add_u32 s20, s20, 0x400000
	s_addc_u32 s21, s21, 0
	global_load_dwordx4 v[132:135], v34, s[20:21]
	global_load_dwordx4 v[136:139], v34, s[20:21] offset:16
	s_add_u32 s20, s20, 0x400000
	s_addc_u32 s21, s21, 0
	global_load_dwordx4 v[140:143], v34, s[20:21]
	global_load_dwordx4 v[144:147], v34, s[20:21] offset:16
	s_add_u32 s20, s20, 0x400000
	s_addc_u32 s21, s21, 0
	global_load_dwordx4 v[148:151], v34, s[20:21]
	global_load_dwordx4 v[152:155], v34, s[20:21] offset:16
	s_add_u32 s20, s20, 0x400000
	s_addc_u32 s21, s21, 0
	global_load_dwordx4 v[156:159], v34, s[20:21]
	global_load_dwordx4 v[160:163], v34, s[20:21] offset:16
	s_add_u32 s20, s20, 0x400000
	s_addc_u32 s21, s21, 0
	global_load_dwordx4 v[164:167], v34, s[20:21]
	global_load_dwordx4 v[168:171], v34, s[20:21] offset:16
	s_add_u32 s20, s20, 0x400000
	s_addc_u32 s21, s21, 0
	global_load_dwordx4 v[172:175], v34, s[20:21]
	global_load_dwordx4 v[176:179], v34, s[20:21] offset:16
	s_add_u32 s20, s20, 0x400000
	s_addc_u32 s21, s21, 0
	global_load_dwordx4 v[180:183], v34, s[20:21]
	global_load_dwordx4 v[184:187], v34, s[20:21] offset:16
	s_add_u32 s20, s20, 0x400000
	s_addc_u32 s21, s21, 0
	global_load_dwordx4 v[188:191], v34, s[20:21]
	global_load_dwordx4 v[192:195], v34, s[20:21] offset:16
	s_add_u32 s20, s20, 0x400000
	s_addc_u32 s21, s21, 0
	s_waitcnt vmcnt(16)
	v_cvt_pk_bf16_f32 v64, v64, v65
	v_cvt_pk_bf16_f32 v65, v66, v67
	v_cvt_pk_bf16_f32 v66, v68, v69
	v_cvt_pk_bf16_f32 v67, v70, v71
	global_store_dwordx4 v35, v[64:67], s[22:23]
	s_add_u32 s22, s22, 0x200000
	s_addc_u32 s23, s23, 0
	v_cvt_pk_bf16_f32 v72, v72, v73
	v_cvt_pk_bf16_f32 v73, v74, v75
	v_cvt_pk_bf16_f32 v74, v76, v77
	v_cvt_pk_bf16_f32 v75, v78, v79
	global_store_dwordx4 v35, v[72:75], s[22:23]
	s_add_u32 s22, s22, 0x200000
	s_addc_u32 s23, s23, 0
	v_cvt_pk_bf16_f32 v80, v80, v81
	v_cvt_pk_bf16_f32 v81, v82, v83
	v_cvt_pk_bf16_f32 v82, v84, v85
	v_cvt_pk_bf16_f32 v83, v86, v87
	global_store_dwordx4 v35, v[80:83], s[22:23]
	s_add_u32 s22, s22, 0x200000
	s_addc_u32 s23, s23, 0
	v_cvt_pk_bf16_f32 v88, v88, v89
	v_cvt_pk_bf16_f32 v89, v90, v91
	v_cvt_pk_bf16_f32 v90, v92, v93
	v_cvt_pk_bf16_f32 v91, v94, v95
	global_store_dwordx4 v35, v[88:91], s[22:23]
	s_add_u32 s22, s22, 0x200000
	s_addc_u32 s23, s23, 0
	v_cvt_pk_bf16_f32 v96, v96, v97
	v_cvt_pk_bf16_f32 v97, v98, v99
	v_cvt_pk_bf16_f32 v98, v100, v101
	v_cvt_pk_bf16_f32 v99, v102, v103
	global_store_dwordx4 v35, v[96:99], s[22:23]
	s_add_u32 s22, s22, 0x200000
	s_addc_u32 s23, s23, 0
	v_cvt_pk_bf16_f32 v104, v104, v105
	v_cvt_pk_bf16_f32 v105, v106, v107
	v_cvt_pk_bf16_f32 v106, v108, v109
	v_cvt_pk_bf16_f32 v107, v110, v111
	global_store_dwordx4 v35, v[104:107], s[22:23]
	s_add_u32 s22, s22, 0x200000
	s_addc_u32 s23, s23, 0
	v_cvt_pk_bf16_f32 v112, v112, v113
	v_cvt_pk_bf16_f32 v113, v114, v115
	v_cvt_pk_bf16_f32 v114, v116, v117
	v_cvt_pk_bf16_f32 v115, v118, v119
	global_store_dwordx4 v35, v[112:115], s[22:23]
	s_add_u32 s22, s22, 0x200000
	s_addc_u32 s23, s23, 0
	v_cvt_pk_bf16_f32 v120, v120, v121
	v_cvt_pk_bf16_f32 v121, v122, v123
	v_cvt_pk_bf16_f32 v122, v124, v125
	v_cvt_pk_bf16_f32 v123, v126, v127
	global_store_dwordx4 v35, v[120:123], s[22:23]
	s_add_u32 s22, s22, 0x200000
	s_addc_u32 s23, s23, 0
	global_load_dwordx4 v[64:67], v34, s[20:21]
	global_load_dwordx4 v[68:71], v34, s[20:21] offset:16
	s_add_u32 s20, s20, 0x400000
	s_addc_u32 s21, s21, 0
	global_load_dwordx4 v[72:75], v34, s[20:21]
	global_load_dwordx4 v[76:79], v34, s[20:21] offset:16
	s_add_u32 s20, s20, 0x400000
	s_addc_u32 s21, s21, 0
	global_load_dwordx4 v[80:83], v34, s[20:21]
	global_load_dwordx4 v[84:87], v34, s[20:21] offset:16
	s_add_u32 s20, s20, 0x400000
	s_addc_u32 s21, s21, 0
	global_load_dwordx4 v[88:91], v34, s[20:21]
	global_load_dwordx4 v[92:95], v34, s[20:21] offset:16
	s_add_u32 s20, s20, 0x400000
	s_addc_u32 s21, s21, 0
	global_load_dwordx4 v[96:99], v34, s[20:21]
	global_load_dwordx4 v[100:103], v34, s[20:21] offset:16
	s_add_u32 s20, s20, 0x400000
	s_addc_u32 s21, s21, 0
	global_load_dwordx4 v[104:107], v34, s[20:21]
	global_load_dwordx4 v[108:111], v34, s[20:21] offset:16
	s_add_u32 s20, s20, 0x400000
	s_addc_u32 s21, s21, 0
	global_load_dwordx4 v[112:115], v34, s[20:21]
	global_load_dwordx4 v[116:119], v34, s[20:21] offset:16
	s_add_u32 s20, s20, 0x400000
	s_addc_u32 s21, s21, 0
	global_load_dwordx4 v[120:123], v34, s[20:21]
	global_load_dwordx4 v[124:127], v34, s[20:21] offset:16
	s_add_u32 s20, s20, 0x400000
	s_addc_u32 s21, s21, 0
	s_waitcnt vmcnt(24)
; __device__ __forceinline__ unsigned pk2(float lo, float hi) { const bf16x2_t v = __builtin_convertvector((f32x2_t){lo, hi}, bf16x2_t); return __builtin_bit_cast(unsigned, v); }
; __device__ __forceinline__ void phase0(LAS unsigned char* lds, int wave) {
;     ...
;     for (size_t i = gt; i < NCH; i += 4 * NT) {
;         f32x4 va[4], vb[4];
; #pragma unroll
;         for (int k = 0; k < 4; ++k) {
;             const size_t ii = i + k * NT;
;             if (ii < NCH) { const size_t e = ii * 8; const float* s = e < (size_t)NPROMPT * DM ? xp + e : xs + (e - (size_t)NPROMPT * DM);
;                 va[k] = *(const f32x4*)s; vb[k] = *(const f32x4*)(s + 4); }
;         }
;         __builtin_amdgcn_sched_barrier(0);
; #pragma unroll
;         for (int k = 0; k < 4; ++k) {
;             const size_t ii = i + k * NT;
;             if (ii < NCH) { u32x4 o; o.x = pk2(va[k].x, va[k].y); o.y = pk2(va[k].z, va[k].w); o.z = pk2(vb[k].x, vb[k].y); o.w = pk2(vb[k].z, vb[k].w);
;                 *(u32x4*)(Xb + ii * 8) = o; }
;         }
	v_cvt_pk_bf16_f32 v132, v132, v133
	v_cvt_pk_bf16_f32 v133, v134, v135
	v_cvt_pk_bf16_f32 v134, v136, v137
	v_cvt_pk_bf16_f32 v135, v138, v139
	global_store_dwordx4 v35, v[132:135], s[22:23]
	s_add_u32 s22, s22, 0x200000
	s_addc_u32 s23, s23, 0
	v_cvt_pk_bf16_f32 v140, v140, v141
	v_cvt_pk_bf16_f32 v141, v142, v143
	v_cvt_pk_bf16_f32 v142, v144, v145
	v_cvt_pk_bf16_f32 v143, v146, v147
	global_store_dwordx4 v35, v[140:143], s[22:23]
	s_add_u32 s22, s22, 0x200000
	s_addc_u32 s23, s23, 0
	v_cvt_pk_bf16_f32 v148, v148, v149
	v_cvt_pk_bf16_f32 v149, v150, v151
	v_cvt_pk_bf16_f32 v150, v152, v153
	v_cvt_pk_bf16_f32 v151, v154, v155
	global_store_dwordx4 v35, v[148:151], s[22:23]
	s_add_u32 s22, s22, 0x200000
	s_addc_u32 s23, s23, 0
	v_cvt_pk_bf16_f32 v156, v156, v157
	v_cvt_pk_bf16_f32 v157, v158, v159
	v_cvt_pk_bf16_f32 v158, v160, v161
	v_cvt_pk_bf16_f32 v159, v162, v163
	global_store_dwordx4 v35, v[156:159], s[22:23]
	s_add_u32 s22, s22, 0x200000
	s_addc_u32 s23, s23, 0
	v_cvt_pk_bf16_f32 v164, v164, v165
	v_cvt_pk_bf16_f32 v165, v166, v167
	v_cvt_pk_bf16_f32 v166, v168, v169
	v_cvt_pk_bf16_f32 v167, v170, v171
	global_store_dwordx4 v35, v[164:167], s[22:23]
	s_add_u32 s22, s22, 0x200000
	s_addc_u32 s23, s23, 0
	v_cvt_pk_bf16_f32 v172, v172, v173
	v_cvt_pk_bf16_f32 v173, v174, v175
	v_cvt_pk_bf16_f32 v174, v176, v177
	v_cvt_pk_bf16_f32 v175, v178, v179
	global_store_dwordx4 v35, v[172:175], s[22:23]
	s_add_u32 s22, s22, 0x200000
	s_addc_u32 s23, s23, 0
	v_cvt_pk_bf16_f32 v180, v180, v181
	v_cvt_pk_bf16_f32 v181, v182, v183
	v_cvt_pk_bf16_f32 v182, v184, v185
	v_cvt_pk_bf16_f32 v183, v186, v187
	global_store_dwordx4 v35, v[180:183], s[22:23]
	s_add_u32 s22, s22, 0x200000
	s_addc_u32 s23, s23, 0
	v_cvt_pk_bf16_f32 v188, v188, v189
	v_cvt_pk_bf16_f32 v189, v190, v191
	v_cvt_pk_bf16_f32 v190, v192, v193
	v_cvt_pk_bf16_f32 v191, v194, v195
	global_store_dwordx4 v35, v[188:191], s[22:23]
	s_add_u32 s22, s22, 0x200000
	s_addc_u32 s23, s23, 0
	global_load_dwordx4 v[132:135], v34, s[20:21]
	global_load_dwordx4 v[136:139], v34, s[20:21] offset:16
	s_add_u32 s20, s20, 0x400000
	s_addc_u32 s21, s21, 0
	global_load_dwordx4 v[140:143], v34, s[20:21]
	global_load_dwordx4 v[144:147], v34, s[20:21] offset:16
	s_add_u32 s20, s20, 0x400000
	s_addc_u32 s21, s21, 0
	global_load_dwordx4 v[148:151], v34, s[20:21]
	global_load_dwordx4 v[152:155], v34, s[20:21] offset:16
	s_add_u32 s20, s20, 0x400000
	s_addc_u32 s21, s21, 0
	global_load_dwordx4 v[156:159], v34, s[20:21]
	global_load_dwordx4 v[160:163], v34, s[20:21] offset:16
	s_add_u32 s20, s20, 0x400000
	s_addc_u32 s21, s21, 0
	global_load_dwordx4 v[164:167], v34, s[20:21]
	global_load_dwordx4 v[168:171], v34, s[20:21] offset:16
	s_add_u32 s20, s20, 0x400000
	s_addc_u32 s21, s21, 0
	global_load_dwordx4 v[172:175], v34, s[20:21]
	global_load_dwordx4 v[176:179], v34, s[20:21] offset:16
	s_add_u32 s20, s20, 0x400000
	s_addc_u32 s21, s21, 0
	global_load_dwordx4 v[180:183], v34, s[20:21]
	global_load_dwordx4 v[184:187], v34, s[20:21] offset:16
	s_add_u32 s20, s20, 0x400000
	s_addc_u32 s21, s21, 0
	global_load_dwordx4 v[188:191], v34, s[20:21]
	global_load_dwordx4 v[192:195], v34, s[20:21] offset:16
	s_add_u32 s20, s20, 0x400000
	s_addc_u32 s21, s21, 0
	s_waitcnt vmcnt(24)
; __device__ __forceinline__ unsigned pk2(float lo, float hi) { const bf16x2_t v = __builtin_convertvector((f32x2_t){lo, hi}, bf16x2_t); return __builtin_bit_cast(unsigned, v); }
; __device__ __forceinline__ void phase0(LAS unsigned char* lds, int wave) {
;     ...
;     for (size_t i = gt; i < NCH; i += 4 * NT) {
;         f32x4 va[4], vb[4];
; #pragma unroll
;         for (int k = 0; k < 4; ++k) {
;             const size_t ii = i + k * NT;
;             if (ii < NCH) { const size_t e = ii * 8; const float* s = e < (size_t)NPROMPT * DM ? xp + e : xs + (e - (size_t)NPROMPT * DM);
;                 va[k] = *(const f32x4*)s; vb[k] = *(const f32x4*)(s + 4); }
;         }
;         __builtin_amdgcn_sched_barrier(0);
; #pragma unroll
;         for (int k = 0; k < 4; ++k) {
;             const size_t ii = i + k * NT;
;             if (ii < NCH) { u32x4 o; o.x = pk2(va[k].x, va[k].y); o.y = pk2(va[k].z, va[k].w); o.z = pk2(vb[k].x, vb[k].y); o.w = pk2(vb[k].z, vb[k].w);
;                 *(u32x4*)(Xb + ii * 8) = o; }
;         }
	v_cvt_pk_bf16_f32 v64, v64, v65
	v_cvt_pk_bf16_f32 v65, v66, v67
	v_cvt_pk_bf16_f32 v66, v68, v69
	v_cvt_pk_bf16_f32 v67, v70, v71
	global_store_dwordx4 v35, v[64:67], s[22:23]
	s_add_u32 s22, s22, 0x200000
	s_addc_u32 s23, s23, 0
	v_cvt_pk_bf16_f32 v72, v72, v73
	v_cvt_pk_bf16_f32 v73, v74, v75
	v_cvt_pk_bf16_f32 v74, v76, v77
	v_cvt_pk_bf16_f32 v75, v78, v79
	global_store_dwordx4 v35, v[72:75], s[22:23]
	s_add_u32 s22, s22, 0x200000
	s_addc_u32 s23, s23, 0
	v_cvt_pk_bf16_f32 v80, v80, v81
	v_cvt_pk_bf16_f32 v81, v82, v83
	v_cvt_pk_bf16_f32 v82, v84, v85
	v_cvt_pk_bf16_f32 v83, v86, v87
	global_store_dwordx4 v35, v[80:83], s[22:23]
	s_add_u32 s22, s22, 0x200000
	s_addc_u32 s23, s23, 0
	v_cvt_pk_bf16_f32 v88, v88, v89
	v_cvt_pk_bf16_f32 v89, v90, v91
	v_cvt_pk_bf16_f32 v90, v92, v93
	v_cvt_pk_bf16_f32 v91, v94, v95
	global_store_dwordx4 v35, v[88:91], s[22:23]
	s_add_u32 s22, s22, 0x200000
	s_addc_u32 s23, s23, 0
	v_cvt_pk_bf16_f32 v96, v96, v97
	v_cvt_pk_bf16_f32 v97, v98, v99
	v_cvt_pk_bf16_f32 v98, v100, v101
	v_cvt_pk_bf16_f32 v99, v102, v103
	global_store_dwordx4 v35, v[96:99], s[22:23]
	s_add_u32 s22, s22, 0x200000
	s_addc_u32 s23, s23, 0
	v_cvt_pk_bf16_f32 v104, v104, v105
	v_cvt_pk_bf16_f32 v105, v106, v107
	v_cvt_pk_bf16_f32 v106, v108, v109
	v_cvt_pk_bf16_f32 v107, v110, v111
	global_store_dwordx4 v35, v[104:107], s[22:23]
	s_add_u32 s22, s22, 0x200000
	s_addc_u32 s23, s23, 0
	v_cvt_pk_bf16_f32 v112, v112, v113
	v_cvt_pk_bf16_f32 v113, v114, v115
	v_cvt_pk_bf16_f32 v114, v116, v117
	v_cvt_pk_bf16_f32 v115, v118, v119
	global_store_dwordx4 v35, v[112:115], s[22:23]
	s_add_u32 s22, s22, 0x200000
	s_addc_u32 s23, s23, 0
	v_cvt_pk_bf16_f32 v120, v120, v121
	v_cvt_pk_bf16_f32 v121, v122, v123
	v_cvt_pk_bf16_f32 v122, v124, v125
	v_cvt_pk_bf16_f32 v123, v126, v127
	global_store_dwordx4 v35, v[120:123], s[22:23]
	s_add_u32 s22, s22, 0x200000
	s_addc_u32 s23, s23, 0
	global_load_dwordx4 v[64:67], v34, s[10:11]
	global_load_dwordx4 v[68:71], v34, s[10:11] offset:16
	s_waitcnt vmcnt(10)
	v_cvt_pk_bf16_f32 v132, v132, v133
	v_cvt_pk_bf16_f32 v133, v134, v135
	v_cvt_pk_bf16_f32 v134, v136, v137
	v_cvt_pk_bf16_f32 v135, v138, v139
	global_store_dwordx4 v35, v[132:135], s[22:23]
	s_add_u32 s22, s22, 0x200000
	s_addc_u32 s23, s23, 0
	v_cvt_pk_bf16_f32 v140, v140, v141
	v_cvt_pk_bf16_f32 v141, v142, v143
	v_cvt_pk_bf16_f32 v142, v144, v145
	v_cvt_pk_bf16_f32 v143, v146, v147
	global_store_dwordx4 v35, v[140:143], s[22:23]
	s_add_u32 s22, s22, 0x200000
	s_addc_u32 s23, s23, 0
	v_cvt_pk_bf16_f32 v148, v148, v149
	v_cvt_pk_bf16_f32 v149, v150, v151
	v_cvt_pk_bf16_f32 v150, v152, v153
	v_cvt_pk_bf16_f32 v151, v154, v155
	global_store_dwordx4 v35, v[148:151], s[22:23]
	s_add_u32 s22, s22, 0x200000
	s_addc_u32 s23, s23, 0
	v_cvt_pk_bf16_f32 v156, v156, v157
	v_cvt_pk_bf16_f32 v157, v158, v159
	v_cvt_pk_bf16_f32 v158, v160, v161
	v_cvt_pk_bf16_f32 v159, v162, v163
	global_store_dwordx4 v35, v[156:159], s[22:23]
	s_add_u32 s22, s22, 0x200000
	s_addc_u32 s23, s23, 0
	v_cvt_pk_bf16_f32 v164, v164, v165
	v_cvt_pk_bf16_f32 v165, v166, v167
	v_cvt_pk_bf16_f32 v166, v168, v169
	v_cvt_pk_bf16_f32 v167, v170, v171
	global_store_dwordx4 v35, v[164:167], s[22:23]
	s_add_u32 s22, s22, 0x200000
	s_addc_u32 s23, s23, 0
	v_cvt_pk_bf16_f32 v172, v172, v173
	v_cvt_pk_bf16_f32 v173, v174, v175
	v_cvt_pk_bf16_f32 v174, v176, v177
	v_cvt_pk_bf16_f32 v175, v178, v179
	global_store_dwordx4 v35, v[172:175], s[22:23]
	s_add_u32 s22, s22, 0x200000
	s_addc_u32 s23, s23, 0
	v_cvt_pk_bf16_f32 v180, v180, v181
	v_cvt_pk_bf16_f32 v181, v182, v183
	v_cvt_pk_bf16_f32 v182, v184, v185
	v_cvt_pk_bf16_f32 v183, v186, v187
	global_store_dwordx4 v35, v[180:183], s[22:23]
	s_add_u32 s22, s22, 0x200000
	s_addc_u32 s23, s23, 0
	v_cvt_pk_bf16_f32 v188, v188, v189
	v_cvt_pk_bf16_f32 v189, v190, v191
	v_cvt_pk_bf16_f32 v190, v192, v193
	v_cvt_pk_bf16_f32 v191, v194, v195
	global_store_dwordx4 v35, v[188:191], s[22:23]
	s_add_u32 s22, s22, 0x200000
	s_addc_u32 s23, s23, 0
	s_waitcnt vmcnt(8)
	v_cvt_pk_bf16_f32 v64, v64, v65
	v_cvt_pk_bf16_f32 v65, v66, v67
	v_cvt_pk_bf16_f32 v66, v68, v69
	v_cvt_pk_bf16_f32 v67, v70, v71
	global_store_dwordx4 v35, v[64:67], s[22:23]
	s_add_u32 s22, s22, 0x200000
	s_addc_u32 s23, s23, 0
